# grid barrier: non-leader workgroups poll the top-level generation word directly instead of waiting for their XCD leader to relay it (one hop shorter release)
# baseline (speedup 1.0000x reference)
; __device__ __forceinline__ unsigned xb_ld(unsigned* p)              { return __hip_atomic_load(p, __ATOMIC_RELAXED, __HIP_MEMORY_SCOPE_AGENT); }
; __device__ __forceinline__ unsigned xb_add(unsigned* p, unsigned v) { return __hip_atomic_fetch_add(p, v, __ATOMIC_RELAXED, __HIP_MEMORY_SCOPE_AGENT); }
; #define XB_SPIN(cond, bar) do { unsigned _sp = 0; while (cond) { __builtin_amdgcn_s_sleep(1); \
;     if ((++_sp & 255u) == 0u) { if (xb_ld(&(bar)[XB_TMO])) break; if (_sp > XB_SPIN_CAP) { atomicAdd(&(bar)[XB_TMO], 1u); break; } } } } while (0)
; __device__ __forceinline__ void xcd_barrier(unsigned* bar, volatile LAS unsigned* st, const Ids I) {
;     ...
;         const unsigned old = xb_add(&bar[XB_XSUB(x)], 1u);
;         const unsigned gen = old / nloc;
;         if (old + 1u == (gen + 1u) * nloc) {
;             __builtin_amdgcn_fence(__ATOMIC_RELEASE, "agent");
;             asm volatile("s_waitcnt vmcnt(0)" ::: "memory");
;             const unsigned og = xb_add(&bar[XB_TOP], 1u);
;             const unsigned tg = og / nx;
;             if (og + 1u == (tg + 1u) * nx) xb_add(&bar[XB_TOPGEN], 1u);
;             else XB_SPIN(xb_ld(&bar[XB_TOPGEN]) == tg, bar);
;             __builtin_amdgcn_fence(__ATOMIC_ACQUIRE, "agent");
;             xb_add(&bar[XB_XGEN(x)], 1u);
;             asm volatile("s_waitcnt vmcnt(0)" ::: "memory");
;         } else {
;             XB_SPIN(xb_ld(&bar[XB_XGEN(x)]) == gen, bar);
.LBB0_77:
	s_or_b64 exec, exec, s[10:11]
	v_cvt_f32_u32_e32 v4, v2
	s_waitcnt vmcnt(0)
	v_readfirstlane_b32 s8, v3
	v_sub_u32_e32 v3, 0, v2
	v_rcp_iflag_f32_e32 v4, v4
	v_add_u32_e32 v5, s8, v1
	v_mul_f32_e32 v4, 0x4f7ffffe, v4
	v_cvt_u32_f32_e32 v4, v4
	v_mul_lo_u32 v1, v3, v4
	v_mul_hi_u32 v1, v4, v1
	v_add_u32_e32 v1, v4, v1
	v_mul_hi_u32 v1, v5, v1
	v_mul_lo_u32 v3, v1, v2
	v_sub_u32_e32 v3, v5, v3
	v_add_u32_e32 v4, 1, v1
	v_cmp_ge_u32_e32 vcc, v3, v2
	s_nop 1
	v_cndmask_b32_e32 v1, v1, v4, vcc
	v_sub_u32_e32 v4, v3, v2
	v_cndmask_b32_e32 v3, v3, v4, vcc
	v_add_u32_e32 v4, 1, v1
	v_cmp_ge_u32_e32 vcc, v3, v2
	v_add_u32_e32 v3, 1, v5
	s_nop 0
	v_cndmask_b32_e32 v1, v1, v4, vcc
	v_mul_lo_u32 v4, v2, v1
	v_add_u32_e32 v2, v4, v2
	v_cmp_ne_u32_e32 vcc, v3, v2
	s_and_saveexec_b64 s[8:9], vcc
	s_xor_b64 s[8:9], exec, s[8:9]
	s_cbranch_execz .LBB0_210
	s_waitcnt lgkmcnt(0)
	s_add_u32 s12, s86, 0x3500
	s_addc_u32 s13, s87, 0
	global_load_dword v0, v145, s[12:13] sc1
	s_waitcnt vmcnt(0)
	v_cmp_eq_u32_e32 vcc, v0, v1
	s_and_saveexec_b64 s[10:11], vcc
	s_cbranch_execz .LBB0_209
	s_mov_b32 s24, 1
	s_mov_b64 s[14:15], 0
	s_branch .LBB0_81
